# stack5 + row-max chain trims + fox-loop packed bias adds split into scalar pairs (all bit-identical instruction-count reductions on serial chains)
# speedup vs baseline: 1.0098x; 1.0051x over previous
.LBB0_251:
	v_add_u32_e32 v0, s18, v225
	ds_read_b64_tr_b16 v[192:193], v0 offset:24576
	ds_read_b64_tr_b16 v[194:195], v0 offset:25088
	v_add_f32_e32 v2, v80, v81
	v_add_f32_e32 v2, v82, v2
	v_add_f32_e32 v2, v83, v2
	v_add_f32_e32 v2, v84, v2
	v_add_f32_e32 v2, v85, v2
	v_cvt_pk_bf16_f32 v156, v80, v81
	v_cvt_pk_bf16_f32 v157, v82, v83
	s_waitcnt lgkmcnt(9)
	v_mfma_f32_32x32x16_bf16 v[96:111], v[188:191], v[140:143], v[48:63]
	ds_read_b64_tr_b16 v[188:189], v0 offset:28672
	ds_read_b64_tr_b16 v[190:191], v0 offset:29184
	v_add_f32_e32 v2, v86, v2
	v_add_f32_e32 v2, v87, v2
	v_add_f32_e32 v2, v88, v2
	v_add_f32_e32 v2, v89, v2
	v_cvt_pk_bf16_f32 v158, v84, v85
	v_cvt_pk_bf16_f32 v159, v86, v87
	s_waitcnt lgkmcnt(10)
	v_mfma_f32_32x32x16_bf16 v[112:127], v[184:187], v[140:143], v[48:63]
	ds_read_b64_tr_b16 v[10:11], v0 offset:25600
	ds_read_b64_tr_b16 v[12:13], v0 offset:26112
	v_add_f32_e32 v2, v90, v2
	v_add_f32_e32 v2, v91, v2
	v_add_f32_e32 v2, v92, v2
	v_add_f32_e32 v2, v93, v2
	v_cvt_pk_bf16_f32 v152, v88, v89
	v_cvt_pk_bf16_f32 v153, v90, v91
	s_waitcnt lgkmcnt(11)
	v_mfma_f32_32x32x16_bf16 v[96:111], v[180:183], v[136:139], v[96:111]
	ds_read_b64_tr_b16 v[180:181], v0 offset:29696
	ds_read_b64_tr_b16 v[182:183], v0 offset:30208
	v_add_f32_e32 v2, v94, v2
	v_add_f32_e32 v2, v95, v2
	v_add_f32_e32 v2, v64, v2
	v_add_f32_e32 v2, v65, v2
	v_cvt_pk_bf16_f32 v154, v92, v93
	v_cvt_pk_bf16_f32 v155, v94, v95
	s_waitcnt lgkmcnt(12)
	v_mfma_f32_32x32x16_bf16 v[112:127], v[176:179], v[136:139], v[112:127]
	ds_read_b64_tr_b16 v[176:177], v0 offset:26624
	ds_read_b64_tr_b16 v[178:179], v0 offset:27136
	v_add_f32_e32 v2, v66, v2
	v_add_f32_e32 v2, v67, v2
	v_add_f32_e32 v2, v68, v2
	v_add_f32_e32 v6, v69, v2
	v_cvt_pk_bf16_f32 v148, v64, v65
	v_cvt_pk_bf16_f32 v149, v66, v67
	s_waitcnt lgkmcnt(13)
	v_mfma_f32_32x32x16_bf16 v[96:111], v[172:175], v[132:135], v[96:111]
	ds_read_b64_tr_b16 v[2:3], v0 offset:30720
	ds_read_b64_tr_b16 v[4:5], v0 offset:31232
	v_add_f32_e32 v6, v70, v6
	v_add_f32_e32 v6, v71, v6
	v_add_f32_e32 v6, v72, v6
	v_add_f32_e32 v14, v73, v6
	v_cvt_pk_bf16_f32 v150, v68, v69
	v_cvt_pk_bf16_f32 v151, v70, v71
	s_waitcnt lgkmcnt(14)
	v_mfma_f32_32x32x16_bf16 v[112:127], v[168:171], v[132:135], v[112:127]
	ds_read_b64_tr_b16 v[6:7], v0 offset:27648
	ds_read_b64_tr_b16 v[8:9], v0 offset:28160
	v_add_f32_e32 v14, v74, v14
	v_add_f32_e32 v14, v75, v14
	v_add_f32_e32 v14, v76, v14
	v_add_f32_e32 v14, v77, v14
	v_cvt_pk_bf16_f32 v144, v72, v73
	v_cvt_pk_bf16_f32 v145, v74, v75
	s_waitcnt lgkmcnt(14)
	v_mfma_f32_32x32x16_bf16 v[96:111], v[164:167], v[128:131], v[96:111]
	ds_read_b64_tr_b16 v[164:165], v0 offset:31744
	ds_read_b64_tr_b16 v[166:167], v0 offset:32256
	v_add_f32_e32 v0, v78, v14
	v_add_f32_e32 v0, v79, v0
	v_add_f32_e32 v0, 0, v0
	v_cvt_pk_bf16_f32 v146, v76, v77
	v_cvt_pk_bf16_f32 v147, v78, v79
	v_mfma_f32_32x32x16_bf16 v[112:127], v[160:163], v[128:131], v[112:127]
	v_lshl_add_u64 v[14:15], v[202:203], 0, s[54:55]
	s_add_i32 s18, s69, s38
	s_mov_b32 s19, m0
	s_mov_b32 m0, s18
	s_nop 0
	global_load_lds_dwordx4 v[14:15], off
	s_mov_b32 m0, s19
	v_lshl_add_u64 v[14:15], v[200:201], 0, s[54:55]
	s_add_i32 s18, s7, s59
	s_mov_b32 s19, m0
	s_mov_b32 m0, s18
	s_nop 0
	global_load_lds_dwordx4 v[14:15], off
	s_mov_b32 m0, s19
	ds_read_b128 v[64:67], v204
	ds_read_b128 v[68:71], v204 offset:32
	ds_read_b128 v[72:75], v204 offset:128
	v_add_f32_e32 v0, v230, v0
	s_waitcnt lgkmcnt(2)
	v_add_f32_e32 v82, v98, v66
	v_add_f32_e32 v83, v99, v67
	s_waitcnt lgkmcnt(1)
	v_add_f32_e32 v84, v100, v68
	v_add_f32_e32 v85, v101, v69
	s_waitcnt lgkmcnt(0)
	v_add_f32_e32 v14, v112, v72
	v_add_f32_e32 v15, v113, v73
	v_add_f32_e32 v66, v114, v74
	v_add_f32_e32 v67, v115, v75
	ds_read_b128 v[72:75], v204 offset:160
	v_add_f32_e32 v86, v102, v70
	v_add_f32_e32 v87, v103, v71
	v_add_f32_e32 v64, v96, v64
	v_add_f32_e32 v65, v97, v65
	v_max3_f32 v81, v82, v83, v15
	v_max_f32_e32 v80, v64, v65
	s_waitcnt lgkmcnt(0)
	v_add_f32_e32 v68, v116, v72
	v_add_f32_e32 v69, v117, v73
	v_add_f32_e32 v70, v118, v74
	v_add_f32_e32 v71, v119, v75
	ds_read_b128 v[72:75], v204 offset:64
	ds_read_b128 v[76:79], v204 offset:192
	v_max3_f32 v80, v80, v14, v66
	v_max3_f32 v80, v80, v67, v84
	v_max3_f32 v81, v81, v86, v87
	s_waitcnt lgkmcnt(1)
	v_add_f32_e32 v88, v104, v72
	v_add_f32_e32 v89, v105, v73
	s_waitcnt lgkmcnt(0)
	v_add_f32_e32 v72, v120, v76
	v_add_f32_e32 v73, v121, v77
	v_add_f32_e32 v90, v106, v74
	v_add_f32_e32 v91, v107, v75
	v_add_f32_e32 v74, v122, v78
	v_add_f32_e32 v75, v123, v79
	ds_read_b128 v[76:79], v204 offset:96
	ds_read_b128 v[94:97], v204 offset:224
	v_max3_f32 v80, v80, v85, v68
	v_max3_f32 v81, v81, v70, v71
	v_max3_f32 v80, v80, v69, v88
	v_max3_f32 v81, v81, v90, v91
	s_waitcnt lgkmcnt(1)
	v_add_f32_e32 v92, v108, v76
	v_add_f32_e32 v93, v109, v77
	s_waitcnt lgkmcnt(0)
	v_add_f32_e32 v76, v124, v94
	v_add_f32_e32 v77, v125, v95
	v_add_f32_e32 v94, v110, v78
	v_add_f32_e32 v95, v111, v79
	v_max3_f32 v80, v80, v89, v72
	v_max3_f32 v81, v81, v74, v75
	v_add_f32_e32 v78, v126, v96
	v_add_f32_e32 v79, v127, v97
	v_max3_f32 v80, v80, v73, v92
	v_max3_f32 v81, v81, v94, v95
	v_max3_f32 v80, v80, v93, v76
	v_max3_f32 v81, v81, v78, v79
	v_max3_f32 v80, v80, v77, v81
	v_mov_b32_e32 v81, v80
	s_nop 1
	v_permlane32_swap_b32_e32 v80, v81
	v_max_f32_e32 v80, v80, v81
	v_cmp_lt_f32_e32 vcc, s96, v80
	s_cmp_lg_u64 vcc, 0
	s_cselect_b64 s[18:19], -1, 0
	s_cbranch_vccnz .LBB0_259

.LBB0_254:
	s_add_i32 s18, s7, 0x2000
	s_cmpk_lg_i32 s7, 0x4000
	s_cselect_b32 s60, s18, 0
	v_add_u32_e32 v14, s69, v225
	ds_read_b64_tr_b16 v[168:169], v14 offset:24576
	ds_read_b64_tr_b16 v[170:171], v14 offset:25088
	v_add_f32_e32 v2, v80, v81
	v_add_f32_e32 v2, v82, v2
	v_add_f32_e32 v2, v83, v2
	v_add_f32_e32 v2, v84, v2
	v_add_f32_e32 v2, v85, v2
	v_cvt_pk_bf16_f32 v156, v80, v81
	v_cvt_pk_bf16_f32 v157, v82, v83
	s_waitcnt lgkmcnt(9)
	v_mfma_f32_32x32x16_bf16 v[96:111], v[112:115], v[140:143], v[48:63]
	ds_read_b64_tr_b16 v[164:165], v14 offset:28672
	ds_read_b64_tr_b16 v[166:167], v14 offset:29184
	v_add_f32_e32 v2, v86, v2
	v_add_f32_e32 v2, v87, v2
	v_add_f32_e32 v2, v88, v2
	v_add_f32_e32 v2, v89, v2
	v_cvt_pk_bf16_f32 v158, v84, v85
	v_cvt_pk_bf16_f32 v159, v86, v87
	s_waitcnt lgkmcnt(10)
	v_mfma_f32_32x32x16_bf16 v[112:127], v[160:163], v[140:143], v[48:63]
	ds_read_b64_tr_b16 v[10:11], v14 offset:25600
	ds_read_b64_tr_b16 v[12:13], v14 offset:26112
	v_add_f32_e32 v2, v90, v2
	v_add_f32_e32 v2, v91, v2
	v_add_f32_e32 v2, v92, v2
	v_add_f32_e32 v2, v93, v2
	v_cvt_pk_bf16_f32 v152, v88, v89
	v_cvt_pk_bf16_f32 v153, v90, v91
	s_waitcnt lgkmcnt(11)
	v_mfma_f32_32x32x16_bf16 v[96:111], v[192:195], v[136:139], v[96:111]
	ds_read_b64_tr_b16 v[160:161], v14 offset:29696
	ds_read_b64_tr_b16 v[162:163], v14 offset:30208
	v_add_f32_e32 v2, v94, v2
	v_add_f32_e32 v2, v95, v2
	v_add_f32_e32 v2, v64, v2
	v_add_f32_e32 v2, v65, v2
	v_cvt_pk_bf16_f32 v154, v92, v93
	v_cvt_pk_bf16_f32 v155, v94, v95
	s_waitcnt lgkmcnt(12)
	v_mfma_f32_32x32x16_bf16 v[112:127], v[188:191], v[136:139], v[112:127]
	ds_read_b64_tr_b16 v[196:197], v14 offset:26624
	ds_read_b64_tr_b16 v[198:199], v14 offset:27136
	v_add_f32_e32 v2, v66, v2
	v_add_f32_e32 v2, v67, v2
	v_add_f32_e32 v2, v68, v2
	v_add_f32_e32 v6, v69, v2
	v_cvt_pk_bf16_f32 v148, v64, v65
	v_cvt_pk_bf16_f32 v149, v66, v67
	s_waitcnt lgkmcnt(13)
	v_mfma_f32_32x32x16_bf16 v[96:111], v[184:187], v[132:135], v[96:111]
	ds_read_b64_tr_b16 v[2:3], v14 offset:30720
	ds_read_b64_tr_b16 v[4:5], v14 offset:31232
	v_add_f32_e32 v6, v70, v6
	v_add_f32_e32 v6, v71, v6
	v_add_f32_e32 v6, v72, v6
	v_add_f32_e32 v15, v73, v6
	v_cvt_pk_bf16_f32 v150, v68, v69
	v_cvt_pk_bf16_f32 v151, v70, v71
	s_waitcnt lgkmcnt(14)
	v_mfma_f32_32x32x16_bf16 v[112:127], v[180:183], v[132:135], v[112:127]
	ds_read_b64_tr_b16 v[6:7], v14 offset:27648
	ds_read_b64_tr_b16 v[8:9], v14 offset:28160
	v_add_f32_e32 v15, v74, v15
	v_add_f32_e32 v15, v75, v15
	v_add_f32_e32 v15, v76, v15
	v_add_f32_e32 v15, v77, v15
	v_cvt_pk_bf16_f32 v144, v72, v73
	v_cvt_pk_bf16_f32 v145, v74, v75
	s_waitcnt lgkmcnt(14)
	v_mfma_f32_32x32x16_bf16 v[96:111], v[176:179], v[128:131], v[96:111]
	ds_read_b64_tr_b16 v[192:193], v14 offset:31744
	ds_read_b64_tr_b16 v[194:195], v14 offset:32256
	v_add_f32_e32 v14, v78, v15
	v_add_f32_e32 v14, v79, v14
	v_add_f32_e32 v80, 0, v14
	v_cvt_pk_bf16_f32 v146, v76, v77
	v_cvt_pk_bf16_f32 v147, v78, v79
	v_mfma_f32_32x32x16_bf16 v[112:127], v[172:175], v[128:131], v[112:127]
	s_add_i32 s18, s7, s38
	s_mov_b32 s19, m0
	s_mov_b32 m0, s18
	s_nop 0
	global_load_lds_dwordx4 v[202:203], off
	s_mov_b32 m0, s19
	s_add_i32 s18, s60, s59
	s_mov_b32 s19, m0
	s_mov_b32 m0, s18
	s_nop 0
	global_load_lds_dwordx4 v[200:201], off
	s_mov_b32 m0, s19
	ds_read_b128 v[64:67], v204 offset:256
	ds_read_b128 v[68:71], v204 offset:288
	ds_read_b128 v[72:75], v204 offset:384
	v_add_f32_e32 v230, v0, v80
	s_waitcnt lgkmcnt(2)
	v_add_f32_e32 v82, v98, v66
	v_add_f32_e32 v83, v99, v67
	s_waitcnt lgkmcnt(1)
	v_add_f32_e32 v84, v100, v68
	v_add_f32_e32 v85, v101, v69
	s_waitcnt lgkmcnt(0)
	s_nop 0
	v_add_f32_e32 v14, v112, v72
	v_add_f32_e32 v15, v113, v73
	v_add_f32_e32 v66, v114, v74
	v_add_f32_e32 v67, v115, v75
	ds_read_b128 v[72:75], v204 offset:416
	v_add_f32_e32 v86, v102, v70
	v_add_f32_e32 v87, v103, v71
	v_add_f32_e32 v64, v96, v64
	v_add_f32_e32 v65, v97, v65
	s_waitcnt lgkmcnt(0)
	v_add_f32_e32 v68, v116, v72
	v_add_f32_e32 v69, v117, v73
	v_add_f32_e32 v70, v118, v74
	v_add_f32_e32 v71, v119, v75
	ds_read_b128 v[72:75], v204 offset:320
	ds_read_b128 v[76:79], v204 offset:448
	v_max_f32_e32 v81, v64, v65
	v_max3_f32 v81, v81, v14, v66
	v_max3_f32 v81, v81, v67, v84
	s_waitcnt lgkmcnt(1)
	v_add_f32_e32 v88, v104, v72
	v_add_f32_e32 v89, v105, v73
	s_waitcnt lgkmcnt(0)
	v_add_f32_e32 v72, v120, v76
	v_add_f32_e32 v73, v121, v77
	v_add_f32_e32 v90, v106, v74
	v_add_f32_e32 v91, v107, v75
	v_add_f32_e32 v74, v122, v78
	v_add_f32_e32 v75, v123, v79
	ds_read_b128 v[76:79], v204 offset:352
	ds_read_b128 v[94:97], v204 offset:480
	v_max3_f32 v81, v81, v85, v68
	v_max3_f32 v81, v81, v69, v88
	v_max3_f32 v81, v81, v89, v72
	s_waitcnt lgkmcnt(1)
	v_add_f32_e32 v92, v108, v76
	v_add_f32_e32 v93, v109, v77
	s_waitcnt lgkmcnt(0)
	v_add_f32_e32 v76, v124, v94
	v_add_f32_e32 v77, v125, v95
	v_add_f32_e32 v94, v110, v78
	v_add_f32_e32 v95, v111, v79
	v_add_f32_e32 v78, v126, v96
	v_add_f32_e32 v79, v127, v97
	v_max3_f32 v96, v82, v83, v15
	v_max3_f32 v96, v96, v86, v87
	v_max3_f32 v96, v96, v70, v71
	v_max3_f32 v96, v96, v90, v91
	v_max3_f32 v96, v96, v74, v75
	v_max3_f32 v81, v81, v73, v92
	v_max3_f32 v96, v96, v94, v95
	v_max3_f32 v81, v81, v93, v76
	v_max3_f32 v96, v96, v78, v79
	v_max3_f32 v0, v81, v77, v96
	v_mov_b32_e32 v80, v0
	s_nop 1
	v_permlane32_swap_b32_e32 v0, v80
	v_max_f32_e32 v0, v0, v80
	v_cmp_lt_f32_e32 vcc, s96, v0
	s_cmp_lg_u64 vcc, 0
	s_cselect_b64 s[18:19], -1, 0
	s_cbranch_vccnz .LBB0_262
